# hgrn_pass_c second MFMA stage: row operands read once, next tile's LDS fragments prefetched (was: every MFMA behind its own LDS round trip); chunk-state loads of that pass hoisted two stages early
# speedup vs baseline: 1.2235x; 1.0104x over previous
.LBB0_1109:
	s_waitcnt vmcnt(6)
	ds_write_b128 v138, v[2:5]
	s_waitcnt vmcnt(5)
	ds_write_b128 v139, v[6:9]
	s_waitcnt vmcnt(4)
	ds_write_b128 v140, v[10:13]
	s_waitcnt vmcnt(3)
	ds_write_b128 v141, v[14:17]
	s_waitcnt vmcnt(2)
	ds_write_b128 v142, v[18:21]
	s_waitcnt vmcnt(1)
	ds_write_b128 v143, v[22:25]
	v_cndmask_b32_e64 v0, v69, v68, s[86:87]
	s_waitcnt lgkmcnt(0)
	s_barrier
	v_mad_u64_u32 v[172:173], s[0:1], v0, s13, v[32:33]
	ds_read_u16 v0, v172 offset:256
	s_waitcnt vmcnt(0)
	s_or_b32 s24, s10, s28
	v_readlane_b32 s25, v255, 20
	v_and_b32_e32 v22, 63, v30
	s_lshl_b32 s88, s24, s25
	s_and_b64 s[24:25], s[86:87], exec
	s_cselect_b32 s24, s95, s33
	s_add_i32 s24, s88, s24
	s_ashr_i32 s25, s24, 31
	s_lshl_b64 s[24:25], s[24:25], 16
	v_readlane_b32 s54, v253, 1
	v_readlane_b32 s55, v253, 2
	v_lshrrev_b32_e32 v23, 6, v30
	v_and_b32_e32 v24, 1, v22
	v_lshrrev_b32_e32 v25, 5, v22
	v_lshl_or_b32 v24, v25, 1, v24
	v_bfe_u32 v25, v22, 1, 4
	v_lshlrev_b32_e32 v22, 9, v25
	v_lshl_add_u32 v22, v24, 4, v22
	v_lshl_add_u32 v22, v23, 6, v22
	s_add_u32 s24, s54, s24
	s_addc_u32 s25, s55, s25
	global_load_dwordx4 v[2:5], v22, s[24:25]
	s_add_u32 s24, s24, 0x2000
	s_addc_u32 s25, s25, 0
	global_load_dwordx4 v[6:9], v22, s[24:25]
	s_add_u32 s24, s24, 0x2000
	s_addc_u32 s25, s25, 0
	global_load_dwordx4 v[10:13], v22, s[24:25]
	s_add_u32 s24, s24, 0x2000
	s_addc_u32 s25, s25, 0
	global_load_dwordx4 v[14:17], v22, s[24:25]
	s_add_u32 s24, s24, 0x2000
	s_addc_u32 s25, s25, 0
	global_load_dwordx4 v[18:21], v22, s[24:25]
	s_add_u32 s24, s24, 0x2000
	s_addc_u32 s25, s25, 0
	global_load_dwordx4 v[22:25], v22, s[24:25]
	v_sub_f32_e32 v178, 1.0, v64
	s_waitcnt lgkmcnt(0)
	v_lshlrev_b32_e32 v0, 16, v0
	v_mul_f32_e32 v0, 0xbfb8aa3b, v0
	v_exp_f32_e32 v0, v0
	s_nop 0
	v_add_f32_e32 v0, 1.0, v0
	v_rcp_f32_e32 v0, v0
	s_nop 0
	v_fma_f32 v26, v178, v0, v64
	v_cndmask_b32_e64 v29, v71, v70, s[86:87]
	v_log_f32_e32 v0, v26
	s_nop 1
	v_mul_f32_e32 v0, 0x3f317217, v0
	ds_read_u16 v28, v172
	ds_read_u16 v27, v172 offset:512
	v_mad_u64_u32 v[172:173], s[0:1], v29, s13, v[32:33]
	ds_read_u16 v29, v172 offset:256
	s_waitcnt lgkmcnt(0)
	v_lshlrev_b32_e32 v29, 16, v29
	v_mul_f32_e32 v29, 0xbfb8aa3b, v29
	v_exp_f32_e32 v29, v29
	s_nop 0
	v_add_f32_e32 v29, 1.0, v29
	v_rcp_f32_e32 v29, v29
	s_nop 0
	v_fma_f32 v41, v178, v29, v64
	v_log_f32_e32 v29, v41
	s_nop 1
	v_mul_f32_e32 v175, 0x3f317217, v29
	ds_read_u16 v171, v172
	ds_read_u16 v29, v172 offset:512
	v_cndmask_b32_e64 v172, v73, v72, s[86:87]
	v_mad_u64_u32 v[180:181], s[0:1], v172, s13, v[32:33]
	ds_read_u16 v172, v180 offset:256
	v_add_f32_e32 v239, v0, v175
	s_waitcnt lgkmcnt(0)
	v_lshlrev_b32_e32 v172, 16, v172
	v_mul_f32_e32 v172, 0xbfb8aa3b, v172
	v_exp_f32_e32 v172, v172
	s_nop 0
	v_add_f32_e32 v172, 1.0, v172
	v_rcp_f32_e32 v172, v172
	s_nop 0
	v_fma_f32 v172, v178, v172, v64
	v_log_f32_e32 v173, v172
	s_nop 1
	v_mul_f32_e32 v176, 0x3f317217, v173
	ds_read_u16 v174, v180
	ds_read_u16 v173, v180 offset:512
	v_cndmask_b32_e64 v180, v75, v74, s[86:87]
	v_mad_u64_u32 v[180:181], s[0:1], v180, s13, v[32:33]
	ds_read_u16 v181, v180 offset:256
	v_add_f32_e32 v238, v239, v176
	v_mov_b32_e32 v176, 0
	s_waitcnt lgkmcnt(0)
	v_lshlrev_b32_e32 v181, 16, v181
	v_mul_f32_e32 v181, 0xbfb8aa3b, v181
	v_exp_f32_e32 v181, v181
	s_nop 0
	v_add_f32_e32 v181, 1.0, v181
	v_rcp_f32_e32 v181, v181
	s_nop 0
	v_fma_f32 v181, v178, v181, v64
	v_log_f32_e32 v188, v181
	s_nop 1
	v_mul_f32_e32 v195, 0x3f317217, v188
	v_cndmask_b32_e64 v189, v77, v76, s[86:87]
	v_mad_u64_u32 v[192:193], s[0:1], v189, s13, v[32:33]
	ds_read_u16 v188, v180
	ds_read_u16 v180, v180 offset:512
	ds_read_u16 v189, v192 offset:256
	v_add_f32_e32 v237, v238, v195
	s_waitcnt lgkmcnt(0)
	v_lshlrev_b32_e32 v189, 16, v189
	v_mul_f32_e32 v189, 0xbfb8aa3b, v189
	v_exp_f32_e32 v189, v189
	s_nop 0
	v_add_f32_e32 v189, 1.0, v189
	v_rcp_f32_e32 v189, v189
	s_nop 0
	v_fma_f32 v190, v178, v189, v64
	v_log_f32_e32 v189, v190
	s_nop 1
	v_mul_f32_e32 v199, 0x3f317217, v189
	ds_read_u16 v191, v192
	ds_read_u16 v189, v192 offset:512
	v_cndmask_b32_e64 v192, v79, v78, s[86:87]
	v_mad_u64_u32 v[196:197], s[0:1], v192, s13, v[32:33]
	ds_read_u16 v192, v196 offset:256
	s_waitcnt lgkmcnt(0)
	v_lshlrev_b32_e32 v192, 16, v192
	v_mul_f32_e32 v192, 0xbfb8aa3b, v192
	v_exp_f32_e32 v192, v192
	s_nop 0
	v_add_f32_e32 v192, 1.0, v192
	v_rcp_f32_e32 v192, v192
	s_nop 0
	v_fma_f32 v192, v178, v192, v64
	v_log_f32_e32 v193, v192
	s_nop 1
	v_mul_f32_e32 v203, 0x3f317217, v193
	ds_read_u16 v194, v196
	ds_read_u16 v193, v196 offset:512
	v_cndmask_b32_e64 v196, v81, v80, s[86:87]
	v_mad_u64_u32 v[196:197], s[0:1], v196, s13, v[32:33]
	ds_read_u16 v197, v196 offset:256
	s_waitcnt lgkmcnt(0)
	v_lshlrev_b32_e32 v197, 16, v197
	v_mul_f32_e32 v197, 0xbfb8aa3b, v197
	v_exp_f32_e32 v197, v197
	s_nop 0
	v_add_f32_e32 v197, 1.0, v197
	v_rcp_f32_e32 v197, v197
	s_nop 0
	v_fma_f32 v197, v178, v197, v64
	v_log_f32_e32 v198, v197
	s_nop 1
	v_mul_f32_e32 v208, 0x3f317217, v198
	v_cndmask_b32_e64 v200, v83, v82, s[86:87]
	v_mad_u64_u32 v[204:205], s[0:1], v200, s13, v[32:33]
	ds_read_u16 v198, v196
	ds_read_u16 v196, v196 offset:512
	ds_read_u16 v200, v204 offset:256
	s_waitcnt lgkmcnt(0)
	v_lshlrev_b32_e32 v200, 16, v200
	v_mul_f32_e32 v200, 0xbfb8aa3b, v200
	v_exp_f32_e32 v200, v200
	s_nop 0
	v_add_f32_e32 v200, 1.0, v200
	v_rcp_f32_e32 v200, v200
	s_nop 0
	v_fma_f32 v200, v178, v200, v64
	v_log_f32_e32 v201, v200
	s_nop 1
	v_mul_f32_e32 v213, 0x3f317217, v201
	ds_read_u16 v201, v204
	ds_read_u16 v202, v204 offset:512
	v_cndmask_b32_e64 v204, v85, v84, s[86:87]
	v_mad_u64_u32 v[204:205], s[0:1], v204, s13, v[32:33]
	ds_read_u16 v205, v204 offset:256
	s_waitcnt lgkmcnt(0)
	v_lshlrev_b32_e32 v205, 16, v205
	v_mul_f32_e32 v205, 0xbfb8aa3b, v205
	v_exp_f32_e32 v205, v205
	s_nop 0
	v_add_f32_e32 v205, 1.0, v205
	v_rcp_f32_e32 v205, v205
	s_nop 0
	v_fma_f32 v205, v178, v205, v64
	v_log_f32_e32 v206, v205
	s_nop 1
	v_mul_f32_e32 v221, 0x3f317217, v206
	v_cndmask_b32_e64 v207, v87, v86, s[86:87]
	v_mad_u64_u32 v[214:215], s[0:1], v207, s13, v[32:33]
	ds_read_u16 v206, v204
	ds_read_u16 v204, v204 offset:512
	ds_read_u16 v207, v214 offset:256
	s_waitcnt lgkmcnt(0)
	v_lshlrev_b32_e32 v207, 16, v207
	v_mul_f32_e32 v207, 0xbfb8aa3b, v207
	v_exp_f32_e32 v207, v207
	s_nop 0
	v_add_f32_e32 v207, 1.0, v207
	v_rcp_f32_e32 v207, v207
	s_nop 0
	v_fma_f32 v209, v178, v207, v64
	v_cndmask_b32_e64 v211, v89, v88, s[86:87]
	v_log_f32_e32 v207, v209
	v_mad_u64_u32 v[216:217], s[0:1], v211, s13, v[32:33]
	v_mul_f32_e32 v225, 0x3f317217, v207
	ds_read_u16 v210, v214
	ds_read_u16 v207, v214 offset:512
	ds_read_u16 v211, v216 offset:256
	s_waitcnt lgkmcnt(0)
	v_lshlrev_b32_e32 v211, 16, v211
	v_mul_f32_e32 v211, 0xbfb8aa3b, v211
	v_exp_f32_e32 v211, v211
	s_nop 0
	v_add_f32_e32 v211, 1.0, v211
	v_rcp_f32_e32 v211, v211
	s_nop 0
	v_fma_f32 v211, v178, v211, v64
	v_cndmask_b32_e64 v215, v91, v90, s[86:87]
	v_log_f32_e32 v212, v211
	v_mad_u64_u32 v[218:219], s[0:1], v215, s13, v[32:33]
	v_mul_f32_e32 v227, 0x3f317217, v212
	ds_read_u16 v214, v216
	ds_read_u16 v212, v216 offset:512
	ds_read_u16 v215, v218 offset:256
	s_waitcnt lgkmcnt(0)
	v_lshlrev_b32_e32 v215, 16, v215
	v_mul_f32_e32 v215, 0xbfb8aa3b, v215
	v_exp_f32_e32 v215, v215
	s_nop 0
	v_add_f32_e32 v215, 1.0, v215
	v_rcp_f32_e32 v215, v215
	s_nop 0
	v_fma_f32 v216, v178, v215, v64
	v_log_f32_e32 v215, v216
	s_nop 1
	v_mul_f32_e32 v240, 0x3f317217, v215
	ds_read_u16 v217, v218
	ds_read_u16 v215, v218 offset:512
	v_cndmask_b32_e64 v218, v93, v92, s[86:87]
	v_mad_u64_u32 v[218:219], s[0:1], v218, s13, v[32:33]
	ds_read_u16 v219, v218 offset:256
	s_waitcnt lgkmcnt(0)
	v_lshlrev_b32_e32 v219, 16, v219
	v_mul_f32_e32 v219, 0xbfb8aa3b, v219
	v_exp_f32_e32 v219, v219
	s_nop 0
	v_add_f32_e32 v219, 1.0, v219
	v_rcp_f32_e32 v219, v219
	s_nop 0
	v_fma_f32 v219, v178, v219, v64
	v_log_f32_e32 v220, v219
	s_nop 1
	v_mul_f32_e32 v241, 0x3f317217, v220
	v_cndmask_b32_e64 v222, v95, v94, s[86:87]
	v_mad_u64_u32 v[228:229], s[0:1], v222, s13, v[32:33]
	ds_read_u16 v220, v218
	ds_read_u16 v218, v218 offset:512
	ds_read_u16 v222, v228 offset:256
	s_waitcnt lgkmcnt(0)
	v_lshlrev_b32_e32 v222, 16, v222
	v_mul_f32_e32 v222, 0xbfb8aa3b, v222
	v_exp_f32_e32 v222, v222
	s_nop 0
	v_add_f32_e32 v222, 1.0, v222
	v_rcp_f32_e32 v222, v222
	s_nop 0
	v_fma_f32 v222, v178, v222, v64
	v_cndmask_b32_e64 v226, v97, v96, s[86:87]
	v_log_f32_e32 v223, v222
	v_mad_u64_u32 v[232:233], s[0:1], v226, s13, v[32:33]
	v_mul_f32_e32 v242, 0x3f317217, v223
	ds_read_u16 v224, v228
	ds_read_u16 v223, v228 offset:512
	ds_read_u16 v226, v232 offset:256
	s_waitcnt lgkmcnt(0)
	v_lshlrev_b32_e32 v226, 16, v226
	v_mul_f32_e32 v226, 0xbfb8aa3b, v226
	v_exp_f32_e32 v226, v226
	s_nop 0
	v_add_f32_e32 v226, 1.0, v226
	v_rcp_f32_e32 v226, v226
	s_nop 0
	v_fma_f32 v228, v178, v226, v64
	v_log_f32_e32 v226, v228
	s_nop 1
	v_mul_f32_e32 v243, 0x3f317217, v226
	v_cndmask_b32_e64 v229, v99, v98, s[86:87]
	v_mad_u64_u32 v[234:235], s[0:1], v229, s13, v[32:33]
	ds_read_u16 v230, v232
	ds_read_u16 v226, v232 offset:512
	ds_read_u16 v229, v234 offset:256
	s_waitcnt lgkmcnt(0)
	v_lshlrev_b32_e32 v229, 16, v229
	v_mul_f32_e32 v229, 0xbfb8aa3b, v229
	v_exp_f32_e32 v229, v229
	s_nop 0
	v_add_f32_e32 v229, 1.0, v229
	v_rcp_f32_e32 v229, v229
	s_nop 0
	v_fma_f32 v232, v178, v229, v64
	v_add_f32_e32 v235, v237, v199
	ds_read_u16 v233, v234
	ds_read_u16 v236, v234 offset:512
	v_log_f32_e32 v178, v232
	v_add_f32_e32 v234, v235, v203
	v_add_f32_e32 v231, v234, v208
	v_mul_f32_e32 v244, 0x3f317217, v178
	v_add_f32_e32 v229, v231, v213
	v_add_f32_e32 v221, v229, v221
	v_add_f32_e32 v213, v221, v225
	v_add_f32_e32 v208, v213, v227
	v_add_f32_e32 v203, v208, v240
	v_add_f32_e32 v199, v203, v241
	v_add_f32_e32 v195, v199, v242
	v_add_f32_e32 v178, v195, v243
	v_add_f32_e32 v175, v178, v244
	ds_write_b32 v101, v175
	s_waitcnt lgkmcnt(0)
	s_barrier
	s_and_saveexec_b64 s[0:1], s[62:63]
	s_cbranch_execnz .LBB0_1156
	s_or_b64 exec, exec, s[0:1]
	s_and_saveexec_b64 s[0:1], s[64:65]
	s_cbranch_execnz .LBB0_1157

.LBB0_1116:
	v_and_b32_e32 v41, 63, v30
	v_lshrrev_b32_e32 v171, 6, v30
	v_and_b32_e32 v188, 1, v41
	v_lshrrev_b32_e32 v189, 5, v41
	v_lshl_or_b32 v188, v189, 1, v188
	v_bfe_u32 v189, v41, 1, 4
	v_lshlrev_b32_e32 v0, 9, v189
	v_lshl_add_u32 v0, v188, 4, v0
	v_lshl_add_u32 v0, v171, 6, v0
	s_mov_b64 s[24:25], s[88:89]
	s_add_u32 s24, s24, 0xc000
	s_addc_u32 s25, s25, 0
	global_load_dwordx4 v[172:175], v0, s[24:25]
	s_add_u32 s24, s24, 0x2000
	s_addc_u32 s25, s25, 0
	global_load_dwordx4 v[26:29], v0, s[24:25]
	v_lshl_add_u32 v171, v171, 2, v188
	v_mul_u32_u24_e32 v171, 0x440, v171
	v_lshl_add_u32 v171, v189, 1, v171
	v_add_u32_e32 v171, s97, v171
	s_waitcnt vmcnt(2)
	v_cvt_pk_bf16_f32 v2, v2, v3
	v_cvt_pk_bf16_f32 v4, v4, v5
	ds_write_b16 v171, v2
	ds_write_b16_d16_hi v171, v2 offset:272
	ds_write_b16 v171, v4 offset:544
	ds_write_b16_d16_hi v171, v4 offset:816
	s_waitcnt vmcnt(2)
	v_cvt_pk_bf16_f32 v6, v6, v7
	v_cvt_pk_bf16_f32 v8, v8, v9
	ds_write_b16 v171, v6 offset:32
	ds_write_b16_d16_hi v171, v6 offset:304
	ds_write_b16 v171, v8 offset:576
	ds_write_b16_d16_hi v171, v8 offset:848
	s_waitcnt vmcnt(2)
	v_cvt_pk_bf16_f32 v10, v10, v11
	v_cvt_pk_bf16_f32 v12, v12, v13
	ds_write_b16 v171, v10 offset:64
	ds_write_b16_d16_hi v171, v10 offset:336
	ds_write_b16 v171, v12 offset:608
	ds_write_b16_d16_hi v171, v12 offset:880
	s_waitcnt vmcnt(2)
	v_cvt_pk_bf16_f32 v14, v14, v15
	v_cvt_pk_bf16_f32 v16, v16, v17
	ds_write_b16 v171, v14 offset:96
	ds_write_b16_d16_hi v171, v14 offset:368
	ds_write_b16 v171, v16 offset:640
	ds_write_b16_d16_hi v171, v16 offset:912
	s_waitcnt vmcnt(2)
	v_cvt_pk_bf16_f32 v18, v18, v19
	v_cvt_pk_bf16_f32 v20, v20, v21
	ds_write_b16 v171, v18 offset:128
	ds_write_b16_d16_hi v171, v18 offset:400
	ds_write_b16 v171, v20 offset:672
	ds_write_b16_d16_hi v171, v20 offset:944
	s_waitcnt vmcnt(2)
	v_cvt_pk_bf16_f32 v22, v22, v23
	v_cvt_pk_bf16_f32 v24, v24, v25
	ds_write_b16 v171, v22 offset:160
	ds_write_b16_d16_hi v171, v22 offset:432
	ds_write_b16 v171, v24 offset:704
	ds_write_b16_d16_hi v171, v24 offset:976
	s_waitcnt vmcnt(1)
	v_cvt_pk_bf16_f32 v172, v172, v173
	v_cvt_pk_bf16_f32 v174, v174, v175
	ds_write_b16 v171, v172 offset:192
	ds_write_b16_d16_hi v171, v172 offset:464
	ds_write_b16 v171, v174 offset:736
	ds_write_b16_d16_hi v171, v174 offset:1008
	s_waitcnt vmcnt(0)
	v_cvt_pk_bf16_f32 v26, v26, v27
	v_cvt_pk_bf16_f32 v28, v28, v29
	ds_write_b16 v171, v26 offset:224
	ds_write_b16_d16_hi v171, v26 offset:496
	ds_write_b16 v171, v28 offset:768
	ds_write_b16_d16_hi v171, v28 offset:1040

.LBB0_1121:
	s_waitcnt lgkmcnt(0)
	s_barrier
	ds_read_b128 v[26:29], v34 offset:17408
	ds_read_b128 v[172:175], v145 offset:34816
	s_mov_b64 s[24:25], -1
	s_and_b64 vcc, exec, s[88:89]
	s_waitcnt lgkmcnt(0)
	v_mfma_f32_16x16x32_bf16 v[26:29], v[26:29], v[172:175], 0
	ds_read_b128 v[172:175], v34 offset:17472
	ds_read_b128 v[188:191], v145 offset:34880
	s_waitcnt lgkmcnt(0)
	v_mfma_f32_16x16x32_bf16 v[26:29], v[172:175], v[188:191], v[26:29]
	ds_read_b128 v[172:175], v34 offset:17536
	ds_read_b128 v[188:191], v145 offset:34944
	s_waitcnt lgkmcnt(0)
	v_mfma_f32_16x16x32_bf16 v[26:29], v[172:175], v[188:191], v[26:29]
	ds_read_b128 v[172:175], v34 offset:17600
	ds_read_b128 v[188:191], v145 offset:35008
	s_waitcnt lgkmcnt(0)
	v_mfma_f32_16x16x32_bf16 v[26:29], v[172:175], v[188:191], v[26:29]
	s_nop 7
	v_cndmask_b32_e64 v0, v26, 0, s[70:71]
	v_cvt_pk_bf16_f32 v0, v0, v0
	ds_write_b16 v146, v0
	v_cndmask_b32_e64 v0, v27, 0, s[72:73]
	v_cvt_pk_bf16_f32 v0, v0, v0
	ds_write_b16 v146, v0 offset:144
	v_cndmask_b32_e64 v0, v28, 0, s[74:75]
	v_cvt_pk_bf16_f32 v0, v0, v0
	ds_write_b16 v146, v0 offset:288
	v_cndmask_b32_e64 v0, v29, 0, s[76:77]
	v_cvt_pk_bf16_f32 v0, v0, v0
	ds_write_b16 v146, v0 offset:432
	ds_read_b128 v[26:29], v34 offset:17408
	ds_read_b128 v[172:175], v145 offset:39168
	s_waitcnt lgkmcnt(0)
	v_mfma_f32_16x16x32_bf16 v[26:29], v[26:29], v[172:175], 0
	ds_read_b128 v[172:175], v34 offset:17472
	ds_read_b128 v[188:191], v145 offset:39232
	s_waitcnt lgkmcnt(0)
	v_mfma_f32_16x16x32_bf16 v[26:29], v[172:175], v[188:191], v[26:29]
	ds_read_b128 v[172:175], v34 offset:17536
	ds_read_b128 v[188:191], v145 offset:39296
	s_waitcnt lgkmcnt(0)
	v_mfma_f32_16x16x32_bf16 v[26:29], v[172:175], v[188:191], v[26:29]
	ds_read_b128 v[172:175], v34 offset:17600
	ds_read_b128 v[188:191], v145 offset:39360
	s_waitcnt lgkmcnt(0)
	v_mfma_f32_16x16x32_bf16 v[26:29], v[172:175], v[188:191], v[26:29]
	s_nop 7
	v_cndmask_b32_e64 v0, v26, 0, s[78:79]
	v_cvt_pk_bf16_f32 v0, v0, v0
	ds_write_b16 v147, v0
	v_cndmask_b32_e64 v0, v27, 0, s[80:81]
	v_cvt_pk_bf16_f32 v0, v0, v0
	ds_write_b16 v147, v0 offset:144
	v_cndmask_b32_e64 v0, v28, 0, s[82:83]
	v_cvt_pk_bf16_f32 v0, v0, v0
	ds_write_b16 v147, v0 offset:288
	v_cndmask_b32_e64 v0, v29, 0, s[84:85]
	v_cvt_pk_bf16_f32 v0, v0, v0
	ds_write_b16 v147, v0 offset:432
	s_waitcnt lgkmcnt(0)
	s_barrier
	ds_read_b128 v[188:191], v34
	ds_read_b128 v[192:195], v34 offset:64
	ds_read_b128 v[196:199], v34 offset:128
	ds_read_b128 v[200:203], v34 offset:192
	ds_read_b128 v[204:207], v35
	ds_read_b128 v[208:211], v35 offset:64
	ds_read_b128 v[212:215], v148
	ds_read_b128 v[216:219], v148 offset:64
	ds_read_b128 v[220:223], v148 offset:128
	ds_read_b128 v[224:227], v148 offset:192
	ds_read_b128 v[244:247], v149 offset:52224
	ds_read_b128 v[248:251], v149 offset:52288
	s_waitcnt lgkmcnt(2)
	v_mfma_f32_16x16x32_bf16 v[26:29], v[188:191], v[212:215], 0
	v_mfma_f32_16x16x32_bf16 v[26:29], v[192:195], v[216:219], v[26:29]
	v_mfma_f32_16x16x32_bf16 v[26:29], v[196:199], v[220:223], v[26:29]
	v_mfma_f32_16x16x32_bf16 v[26:29], v[200:203], v[224:227], v[26:29]
	ds_read_b128 v[228:231], v148 offset:4352
	ds_read_b128 v[232:235], v148 offset:4416
	ds_read_b128 v[236:239], v148 offset:4480
	ds_read_b128 v[240:243], v148 offset:4544
	s_waitcnt lgkmcnt(4)
	v_mfma_f32_16x16x32_bf16 v[26:29], v[204:207], v[244:247], v[26:29]
	v_mfma_f32_16x16x32_bf16 v[26:29], v[208:211], v[248:251], v[26:29]
	s_cbranch_vccnz .LBB0_1161
	s_andn2_b64 vcc, exec, s[24:25]
	v_add_u32_e32 v0, v111, v113
	s_cbranch_vccz .LBB0_1162

.LBB0_1130:
	s_mov_b64 s[24:25], -1
	s_and_b64 vcc, exec, s[0:1]
	ds_read_b128 v[244:247], v149 offset:54528
	ds_read_b128 v[248:251], v149 offset:54592
	s_waitcnt lgkmcnt(2)
	v_mfma_f32_16x16x32_bf16 v[26:29], v[188:191], v[228:231], 0
	v_mfma_f32_16x16x32_bf16 v[26:29], v[192:195], v[232:235], v[26:29]
	v_mfma_f32_16x16x32_bf16 v[26:29], v[196:199], v[236:239], v[26:29]
	v_mfma_f32_16x16x32_bf16 v[26:29], v[200:203], v[240:243], v[26:29]
	ds_read_b128 v[212:215], v148 offset:8704
	ds_read_b128 v[216:219], v148 offset:8768
	ds_read_b128 v[220:223], v148 offset:8832
	ds_read_b128 v[224:227], v148 offset:8896
	s_waitcnt lgkmcnt(4)
	v_mfma_f32_16x16x32_bf16 v[26:29], v[204:207], v[244:247], v[26:29]
	v_mfma_f32_16x16x32_bf16 v[26:29], v[208:211], v[248:251], v[26:29]
	s_cbranch_vccz .LBB0_1168
	s_andn2_b64 vcc, exec, s[24:25]
	v_add_u32_e32 v0, v117, v113
	s_cbranch_vccz .LBB0_1169

.LBB0_1139:
	s_mov_b64 s[24:25], -1
	s_and_b64 vcc, exec, s[0:1]
	ds_read_b128 v[244:247], v149 offset:56832
	ds_read_b128 v[248:251], v149 offset:56896
	s_waitcnt lgkmcnt(2)
	v_mfma_f32_16x16x32_bf16 v[26:29], v[188:191], v[212:215], 0
	v_mfma_f32_16x16x32_bf16 v[26:29], v[192:195], v[216:219], v[26:29]
	v_mfma_f32_16x16x32_bf16 v[26:29], v[196:199], v[220:223], v[26:29]
	v_mfma_f32_16x16x32_bf16 v[26:29], v[200:203], v[224:227], v[26:29]
	ds_read_b128 v[228:231], v148 offset:13056
	ds_read_b128 v[232:235], v148 offset:13120
	ds_read_b128 v[236:239], v148 offset:13184
	ds_read_b128 v[240:243], v148 offset:13248
	s_waitcnt lgkmcnt(4)
	v_mfma_f32_16x16x32_bf16 v[26:29], v[204:207], v[244:247], v[26:29]
	v_mfma_f32_16x16x32_bf16 v[26:29], v[208:211], v[248:251], v[26:29]
	s_cbranch_vccz .LBB0_1175
	s_andn2_b64 vcc, exec, s[24:25]
	v_add_u32_e32 v0, v118, v113
	s_cbranch_vccz .LBB0_1176

.LBB0_1148:
	s_mov_b64 s[24:25], -1
	s_and_b64 vcc, exec, s[0:1]
	ds_read_b128 v[244:247], v149 offset:59136
	ds_read_b128 v[248:251], v149 offset:59200
	s_waitcnt lgkmcnt(2)
	v_mfma_f32_16x16x32_bf16 v[26:29], v[188:191], v[228:231], 0
	v_mfma_f32_16x16x32_bf16 v[26:29], v[192:195], v[232:235], v[26:29]
	v_mfma_f32_16x16x32_bf16 v[26:29], v[196:199], v[236:239], v[26:29]
	v_mfma_f32_16x16x32_bf16 v[26:29], v[200:203], v[240:243], v[26:29]
	s_waitcnt lgkmcnt(0)
	v_mfma_f32_16x16x32_bf16 v[26:29], v[204:207], v[244:247], v[26:29]
	v_mfma_f32_16x16x32_bf16 v[26:29], v[208:211], v[248:251], v[26:29]
	s_cbranch_vccz .LBB0_1182
	s_andn2_b64 vcc, exec, s[24:25]
	v_add_u32_e32 v0, v119, v113
	s_cbranch_vccz .LBB0_1183
